# DA LDS-DMA global addresses formed with scalar adds (saddr form) instead of 64-bit vector adds
# speedup vs baseline: 1.0124x; 1.0124x over previous
; #define LAS __attribute__((address_space(3)))
; __device__ __forceinline__ void finishSM(f32x16& p0, f32x16& p1, float alpha, float& l_reg, bf16x8& pa0, bf16x8& pa1, bf16x8& pa2, bf16x8& pa3) {
; #pragma unroll
;     for (int r = 0; r < 16; ++r) p1[r] = __builtin_amdgcn_exp2f(p1[r]);
;     typedef float f32x2 __attribute__((ext_vector_type(2)));
;     f32x2 s2 = (f32x2){p0[0], p0[1]};
; #pragma unroll
;     for (int r = 2; r < 16; r += 2) s2 += (f32x2){p0[r], p0[r + 1]};
; #pragma unroll
;     for (int r = 0; r < 16; r += 2) s2 += (f32x2){p1[r], p1[r + 1]};
;     float ps = s2.x + s2.y;
;     { auto rr = __builtin_amdgcn_permlane32_swap(__float_as_uint(ps), __float_as_uint(ps), false, false);
;       ps = __uint_as_float(rr[0]) + __uint_as_float(rr[1]); }
;     l_reg = l_reg * alpha + ps;
;     ...
;     PK4(p0, 0, pa0); PK4(p0, 8, pa1); PK4(p1, 0, pa2); PK4(p1, 8, pa3);
;     ...
; }
; template <int MODE> __device__ __forceinline__ void qkt(f32x16& p0, f32x16& p1, const LAS unsigned char* Kt, const LAS unsigned char* Krt, const bf16x8* qr, int r32, int hi, int comp) {
;     p0 = f32x16{}; p1 = f32x16{};
;     constexpr int NDN = MODE ? 8 : 4;
; #pragma unroll
;     for (int d0 = 0; d0 < NDN; ++d0) { const int cb = ((MODE ? 0 : comp * 64) + d0 * 16 + hi * 8) * 2;
;         const bf16x8 b0 = *(const LAS bf16x8*)(Kt + KSWZ(r32, cb));
;         const bf16x8 b1 = *(const LAS bf16x8*)(Kt + KSWZ(32 + r32, cb));
;         p0 = __builtin_amdgcn_mfma_f32_32x32x16_bf16(b0, qr[d0], p0, 0, 0, 0);
;         p1 = __builtin_amdgcn_mfma_f32_32x32x16_bf16(b1, qr[d0], p1, 0, 0, 0); }
.LBB0_541:
	s_mov_b32 s93, s92
	s_mov_b32 s92, s2
	s_andn2_b64 s[2:3], exec, s[48:49]
	s_andn2_b64 vcc, exec, s[48:49]
	s_cbranch_vccnz .LBB0_543
	s_add_u32 s98, s66, s24
	s_addc_u32 s99, s67, s25
	s_mov_b32 m0, s85
	s_add_u32 s100, s66, 0x3561000
	global_load_lds_dwordx4 v158, s[98:99]
	s_mov_b32 m0, s84
	s_addc_u32 s101, s67, 0
	global_load_lds_dwordx4 v156, s[98:99]
	s_add_i32 s16, s89, s31
	s_mov_b32 m0, s16
	s_nop 0
	global_load_lds_dwordx4 v154, s[100:101]
	s_add_u32 s100, s100, 0x80
	s_addc_u32 s101, s101, 0
	s_add_i32 m0, s16, 0x400
	s_nop 0
	global_load_lds_dwordx4 v154, s[100:101]
.LBB0_543:
	v_add_u32_e32 v181, v180, v171
	ds_read_b128 v[96:99], v181
	ds_read_b128 v[112:115], v181 offset:8192
	v_add_u32_e32 v182, v180, v173
	v_add_u32_e32 v183, v180, v175
	v_add_u32_e32 v184, v180, v177
	ds_read_b128 v[188:191], v182
	ds_read_b128 v[192:195], v182 offset:8192
	ds_read_b128 v[200:203], v183
	ds_read_b128 v[204:207], v183 offset:8192
	ds_read_b128 v[208:211], v184
	ds_read_b128 v[212:215], v184 offset:8192
	v_exp_f32_e32 v196, v84
	v_exp_f32_e32 v197, v85
	v_pk_add_f32 v[84:85], v[64:65], v[66:67]
	s_waitcnt lgkmcnt(0)
	v_mfma_f32_32x32x16_bf16 v[96:111], v[96:99], v[140:143], v[216:231]
	v_add_f32_e64 v84, v68, v84
	v_add_f32_e64 v85, v69, v85
	v_exp_f32_e32 v80, v80
	v_pk_add_f32 v[84:85], v[70:71], v[84:85]
	v_exp_f32_e32 v81, v81
	v_pk_add_f32 v[84:85], v[72:73], v[84:85]
	v_exp_f32_e32 v82, v82
	v_exp_f32_e32 v83, v83
	v_mfma_f32_32x32x16_bf16 v[112:127], v[112:115], v[140:143], v[216:231]
	v_add_f32_e64 v84, v74, v84
	v_add_f32_e64 v85, v75, v85
	v_exp_f32_e32 v198, v86
	v_pk_add_f32 v[84:85], v[76:77], v[84:85]
	v_exp_f32_e32 v199, v87
	v_pk_add_f32 v[84:85], v[78:79], v[84:85]
	v_exp_f32_e32 v88, v88
	v_exp_f32_e32 v89, v89
	v_mfma_f32_32x32x16_bf16 v[96:111], v[188:191], v[136:139], v[96:111]
	v_add_f32_e64 v84, v80, v84
	v_add_f32_e64 v85, v81, v85
	v_exp_f32_e32 v90, v90
	v_exp_f32_e32 v91, v91
	v_pk_add_f32 v[84:85], v[82:83], v[84:85]
	v_exp_f32_e32 v92, v92
	v_exp_f32_e32 v93, v93
	v_pk_add_f32 v[84:85], v[196:197], v[84:85]
	v_mfma_f32_32x32x16_bf16 v[112:127], v[192:195], v[136:139], v[112:127]
	v_exp_f32_e32 v94, v94
	v_exp_f32_e32 v95, v95
	v_pk_add_f32 v[84:85], v[198:199], v[84:85]
	s_nop 0
	v_pk_add_f32 v[84:85], v[88:89], v[84:85]
	s_nop 0
	v_pk_add_f32 v[84:85], v[90:91], v[84:85]
	v_mfma_f32_32x32x16_bf16 v[96:111], v[200:203], v[132:135], v[96:111]
	v_add_f32_e64 v84, v92, v84
	v_add_f32_e64 v85, v93, v85
	v_add_f32_e64 v84, v94, v84
	v_add_f32_e64 v85, v95, v85
	v_add_f32_e64 v162, v84, v85
	v_add_f32_e64 v163, v85, v84
	v_cvt_pk_bf16_f32 v84, v64, v65
	v_cvt_pk_bf16_f32 v85, v66, v67
	v_mfma_f32_32x32x16_bf16 v[112:127], v[204:207], v[132:135], v[112:127]
	v_mov_b32_e32 v187, v162
	v_cvt_pk_bf16_f32 v86, v68, v69
	v_cvt_pk_bf16_f32 v87, v70, v71
	v_cvt_pk_bf16_f32 v72, v72, v73
	v_cvt_pk_bf16_f32 v73, v74, v75
	v_cvt_pk_bf16_f32 v74, v76, v77
	v_cvt_pk_bf16_f32 v75, v78, v79
	v_mfma_f32_32x32x16_bf16 v[96:111], v[208:211], v[128:131], v[96:111]
	v_cvt_pk_bf16_f32 v76, v80, v81
	v_cvt_pk_bf16_f32 v77, v82, v83
	v_cvt_pk_bf16_f32 v78, v196, v197
	v_cvt_pk_bf16_f32 v79, v198, v199
	v_cvt_pk_bf16_f32 v80, v88, v89
	v_cvt_pk_bf16_f32 v81, v90, v91
	v_cvt_pk_bf16_f32 v82, v92, v93
	v_mfma_f32_32x32x16_bf16 v[112:127], v[212:215], v[128:131], v[112:127]
	v_cvt_pk_bf16_f32 v83, v94, v95
	v_permlane32_swap_b32_e32 v162, v187
	s_andn2_b64 s[4:5], exec, s[62:63]
	s_andn2_b64 vcc, exec, s[62:63]
	s_cbranch_vccnz .LBB0_545
	s_waitcnt vmcnt(0) lgkmcnt(0)
	s_barrier

.LBB0_551:
	s_andn2_b64 vcc, exec, s[68:69]
	s_cbranch_vccnz .LBB0_553
	s_add_u32 s98, s66, s26
	s_addc_u32 s99, s67, s27
	s_mov_b32 m0, s90
	s_add_u32 s100, s66, 0x35c1000
	global_load_lds_dwordx4 v158, s[98:99]
	s_mov_b32 m0, s91
	s_addc_u32 s101, s67, 0
	global_load_lds_dwordx4 v156, s[98:99]
	s_add_i32 s16, s89, s92
	s_mov_b32 m0, s16
	s_nop 0
	global_load_lds_dwordx4 v154, s[100:101]
	s_add_u32 s100, s100, 0x80
	s_addc_u32 s101, s101, 0
	s_add_i32 m0, s16, 0x400
	s_nop 0
	global_load_lds_dwordx4 v154, s[100:101]
.LBB0_553:
	s_and_b64 vcc, exec, s[2:3]
	s_cbranch_vccnz .LBB0_555
	s_add_u32 s98, s66, s26
	s_addc_u32 s99, s67, s27
	s_mov_b32 m0, s90
	s_add_u32 s100, s66, 0x35c1000
	global_load_lds_dwordx4 v158, s[98:99]
	s_mov_b32 m0, s91
	s_addc_u32 s101, s67, 0
	global_load_lds_dwordx4 v156, s[98:99]
	s_add_i32 s16, s89, s92
	s_mov_b32 m0, s16
	s_nop 0
	global_load_lds_dwordx4 v154, s[100:101]
	s_add_u32 s100, s100, 0x80
	s_addc_u32 s101, s101, 0
	s_add_i32 m0, s16, 0x400
	s_nop 0
	global_load_lds_dwordx4 v154, s[100:101]

.LBB0_563:
	s_andn2_b64 vcc, exec, s[68:69]
	s_cbranch_vccnz .LBB0_567
	s_cmp_ge_u32 s30, s29
	s_cbranch_scc1 .LBB0_566
	s_add_u32 s98, s66, s40
	s_addc_u32 s99, s67, s41
	s_mov_b32 m0, s85
	s_nop 0
	global_load_lds_dwordx4 v158, s[98:99]
	s_mov_b32 m0, s84
	s_nop 0
	global_load_lds_dwordx4 v156, s[98:99]
.LBB0_566:
	s_add_u32 s100, s66, 0x3621000
	s_addc_u32 s101, s67, 0
	s_add_i32 s68, s89, s93
	s_mov_b32 m0, s68
	s_nop 0
	global_load_lds_dwordx4 v154, s[100:101]
	s_add_u32 s100, s100, 0x80
	s_addc_u32 s101, s101, 0
	s_add_i32 m0, s68, 0x400
	s_nop 0
	global_load_lds_dwordx4 v154, s[100:101]

.LBB0_569:
	s_nop 0
	v_sub_f32_e32 v186, 0, v216
	s_and_b64 vcc, exec, s[2:3]
	s_cbranch_vccnz .LBB0_573
	s_cmp_ge_u32 s30, s29
	s_cbranch_scc1 .LBB0_572
	s_mul_i32 s2, s30, 0x60000
	s_mul_hi_u32 s3, s30, 0x60000
	s_add_u32 s2, s64, s2
	s_addc_u32 s3, s65, s3
	v_lshl_add_u64 v[96:97], s[2:3], 0, v[146:147]
	s_mov_b32 m0, s85
	v_lshl_add_u64 v[96:97], v[96:97], 0, s[20:21]
	global_load_lds_dwordx4 v[96:97], off
	v_lshl_add_u64 v[96:97], s[2:3], 0, v[152:153]
	v_lshl_add_u64 v[96:97], v[96:97], 0, s[20:21]
	s_mov_b32 m0, s84
	s_nop 0
	global_load_lds_dwordx4 v[96:97], off

; __global__ void __launch_bounds__(NWAVES * 64, 2) fwd_mega(Args a) {
	.amdhsa_kernel _Z8fwd_mega4Args
		.amdhsa_group_segment_fixed_size 0
		.amdhsa_private_segment_fixed_size 0
		.amdhsa_kernarg_size 440
		.amdhsa_user_sgpr_count 2
		.amdhsa_user_sgpr_dispatch_ptr 0
		.amdhsa_user_sgpr_queue_ptr 0
		.amdhsa_user_sgpr_kernarg_segment_ptr 1
		.amdhsa_user_sgpr_dispatch_id 0
		.amdhsa_user_sgpr_kernarg_preload_length 0
		.amdhsa_user_sgpr_kernarg_preload_offset 0
		.amdhsa_user_sgpr_private_segment_size 0
		.amdhsa_uses_dynamic_stack 0
		.amdhsa_enable_private_segment 0
		.amdhsa_system_sgpr_workgroup_id_x 1
		.amdhsa_system_sgpr_workgroup_id_y 0
		.amdhsa_system_sgpr_workgroup_id_z 0
		.amdhsa_system_sgpr_workgroup_info 0
		.amdhsa_system_vgpr_workitem_id 2
		.amdhsa_next_free_vgpr 256
		.amdhsa_next_free_sgpr 102
		.amdhsa_accum_offset 256
		.amdhsa_reserve_vcc 1
		.amdhsa_float_round_mode_32 0
		.amdhsa_float_round_mode_16_64 0
		.amdhsa_float_denorm_mode_32 3
		.amdhsa_float_denorm_mode_16_64 3
		.amdhsa_dx10_clamp 1
		.amdhsa_ieee_mode 1
		.amdhsa_fp16_overflow 0
		.amdhsa_tg_split 0
		.amdhsa_exception_fp_ieee_invalid_op 0
		.amdhsa_exception_fp_denorm_src 0
		.amdhsa_exception_fp_ieee_div_zero 0
		.amdhsa_exception_fp_ieee_overflow 0
		.amdhsa_exception_fp_ieee_underflow 0
		.amdhsa_exception_fp_ieee_inexact 0
		.amdhsa_exception_int_div_zero 0
	.end_amdhsa_kernel

; __global__ void __launch_bounds__(NWAVES * 64, 2) fwd_mega(Args a) {
amdhsa.kernels:
  - .agpr_count:     0
    .args:
      - .offset:         0
        .size:           184
        .value_kind:     by_value
      - .offset:         184
        .size:           4
        .value_kind:     hidden_block_count_x
      - .offset:         188
        .size:           4
        .value_kind:     hidden_block_count_y
      - .offset:         192
        .size:           4
        .value_kind:     hidden_block_count_z
      - .offset:         196
        .size:           2
        .value_kind:     hidden_group_size_x
      - .offset:         198
        .size:           2
        .value_kind:     hidden_group_size_y
      - .offset:         200
        .size:           2
        .value_kind:     hidden_group_size_z
      - .offset:         202
        .size:           2
        .value_kind:     hidden_remainder_x
      - .offset:         204
        .size:           2
        .value_kind:     hidden_remainder_y
      - .offset:         206
        .size:           2
        .value_kind:     hidden_remainder_z
      - .offset:         224
        .size:           8
        .value_kind:     hidden_global_offset_x
      - .offset:         232
        .size:           8
        .value_kind:     hidden_global_offset_y
      - .offset:         240
        .size:           8
        .value_kind:     hidden_global_offset_z
      - .offset:         248
        .size:           2
        .value_kind:     hidden_grid_dims
      - .offset:         272
        .size:           8
        .value_kind:     hidden_multigrid_sync_arg
      - .offset:         304
        .size:           4
        .value_kind:     hidden_dynamic_lds_size
    .group_segment_fixed_size: 0
    .kernarg_segment_align: 8
    .kernarg_segment_size: 440
    .language:       OpenCL C
    .language_version:
      - 2
      - 0
    .max_flat_workgroup_size: 512
    .name:           _Z8fwd_mega4Args
    .private_segment_fixed_size: 0
    .sgpr_count:     108
    .sgpr_spill_count: 9
    .symbol:         _Z8fwd_mega4Args.kd
    .uniform_work_group_size: 1
    .uses_dynamic_stack: false
    .vgpr_count:     256
    .vgpr_spill_count: 0
    .wavefront_size: 64
